# norm2+router phases: s_setprio 2 for wave 0 (the only wave that can own two row tiles), reset at the phase end
# speedup vs baseline: 1.0136x; 1.0136x over previous
.LBB0_506:
	s_cmp_gt_i32 s60, 7
	s_cselect_b64 s[4:5], -1, 0
	s_cmp_lt_i32 s61, 8
	s_cselect_b64 s[6:7], -1, 0
	s_or_b64 s[4:5], s[4:5], s[6:7]
	s_and_b64 vcc, exec, s[4:5]
	s_cbranch_vccnz .LBB0_600
	v_readlane_b32 s100, v255, 6
	s_cmp_lg_u32 s100, 0
	s_cbranch_scc1 .Ln2prio_3
	s_setprio 2
.Ln2prio_3:
	s_mul_hi_i32 s5, s2, 0x880
	s_mul_i32 s4, s2, 0x880
	s_ashr_i32 s57, s56, 31
	s_or_b64 s[6:7], s[4:5], s[56:57]
	s_mov_b32 s6, 0
	v_and_b32_e32 v196, 63, v0
	s_cmp_lg_u64 s[6:7], 0
	s_cbranch_scc0 .LBB0_560
	s_ashr_i32 s8, s57, 31
	s_add_u32 s6, s56, s8
	s_mov_b32 s9, s8
	s_addc_u32 s7, s57, s8
	s_xor_b64 s[10:11], s[6:7], s[8:9]
	v_cvt_f32_u32_e32 v1, s10
	v_cvt_f32_u32_e32 v2, s11
	s_sub_u32 s3, 0, s10
	s_subb_u32 s14, 0, s11
	v_fmamk_f32 v1, v2, 0x4f800000, v1
	v_rcp_f32_e32 v1, v1
	s_nop 0
	v_mul_f32_e32 v1, 0x5f7ffffc, v1
	v_mul_f32_e32 v2, 0x2f800000, v1
	v_trunc_f32_e32 v2, v2
	v_fmamk_f32 v1, v2, 0xcf800000, v1
	v_cvt_u32_f32_e32 v2, v2
	v_cvt_u32_f32_e32 v1, v1
	v_readfirstlane_b32 s15, v2
	v_readfirstlane_b32 s12, v1
	s_mul_i32 s13, s3, s15
	s_mul_hi_u32 s17, s3, s12
	s_mul_i32 s16, s14, s12
	s_add_i32 s13, s17, s13
	s_add_i32 s13, s13, s16
	s_mul_i32 s18, s3, s12
	s_mul_i32 s17, s12, s13
	s_mul_hi_u32 s19, s12, s18
	s_mul_hi_u32 s16, s12, s13
	s_add_u32 s17, s19, s17
	s_addc_u32 s16, 0, s16
	s_mul_hi_u32 s20, s15, s18
	s_mul_i32 s18, s15, s18
	s_add_u32 s17, s17, s18
	s_mul_hi_u32 s19, s15, s13
	s_addc_u32 s16, s16, s20
	s_addc_u32 s17, s19, 0
	s_mul_i32 s13, s15, s13
	s_add_u32 s13, s16, s13
	s_addc_u32 s16, 0, s17
	s_add_u32 s17, s12, s13
	s_cselect_b64 s[12:13], -1, 0
	s_cmp_lg_u64 s[12:13], 0
	s_addc_u32 s15, s15, s16
	s_mul_i32 s12, s3, s15
	s_mul_hi_u32 s13, s3, s17
	s_add_i32 s12, s13, s12
	s_mul_i32 s14, s14, s17
	s_add_i32 s12, s12, s14
	s_mul_i32 s3, s3, s17
	s_mul_hi_u32 s14, s15, s3
	s_mul_i32 s16, s15, s3
	s_mul_i32 s19, s17, s12
	s_mul_hi_u32 s3, s17, s3
	s_mul_hi_u32 s18, s17, s12
	s_add_u32 s3, s3, s19
	s_addc_u32 s18, 0, s18
	s_add_u32 s3, s3, s16
	s_mul_hi_u32 s13, s15, s12
	s_addc_u32 s3, s18, s14
	s_addc_u32 s13, s13, 0
	s_mul_i32 s12, s15, s12
	s_add_u32 s3, s3, s12
	s_addc_u32 s14, 0, s13
	s_add_u32 s3, s17, s3
	s_cselect_b64 s[12:13], -1, 0
	s_cmp_lg_u64 s[12:13], 0
	s_addc_u32 s16, s15, s14
	s_ashr_i32 s12, s5, 31
	s_add_u32 s14, s4, s12
	s_mov_b32 s13, s12
	s_addc_u32 s15, s5, s12
	s_xor_b64 s[14:15], s[14:15], s[12:13]
	s_mul_i32 s17, s14, s16
	s_mul_hi_u32 s18, s14, s3
	s_mul_hi_u32 s5, s14, s16
	s_add_u32 s17, s18, s17
	s_addc_u32 s5, 0, s5
	s_mul_hi_u32 s19, s15, s3
	s_mul_i32 s3, s15, s3
	s_add_u32 s3, s17, s3
	s_mul_hi_u32 s18, s15, s16
	s_addc_u32 s3, s5, s19
	s_addc_u32 s5, s18, 0
	s_mul_i32 s16, s15, s16
	s_add_u32 s3, s3, s16
	s_addc_u32 s5, 0, s5
	s_mul_i32 s16, s10, s5
	s_mul_hi_u32 s17, s10, s3
	s_add_i32 s16, s17, s16
	s_mul_i32 s17, s11, s3
	s_add_i32 s20, s16, s17
	s_sub_i32 s18, s15, s20
	s_mul_i32 s16, s10, s3
	s_sub_u32 s14, s14, s16
	s_cselect_b64 s[16:17], -1, 0
	s_cmp_lg_u64 s[16:17], 0
	s_subb_u32 s21, s18, s11
	s_sub_u32 s22, s14, s10
	s_cselect_b64 s[18:19], -1, 0
	s_cmp_lg_u64 s[18:19], 0
	s_subb_u32 s18, s21, 0
	s_cmp_ge_u32 s18, s11
	s_cselect_b32 s19, -1, 0
	s_cmp_ge_u32 s22, s10
	s_cselect_b32 s21, -1, 0
	s_cmp_eq_u32 s18, s11
	s_cselect_b32 s18, s21, s19
	s_add_u32 s19, s3, 1
	s_addc_u32 s21, s5, 0
	s_add_u32 s22, s3, 2
	s_addc_u32 s23, s5, 0
	s_cmp_lg_u32 s18, 0
	s_cselect_b32 s18, s22, s19
	s_cselect_b32 s19, s23, s21
	s_cmp_lg_u64 s[16:17], 0
	s_subb_u32 s15, s15, s20
	s_cmp_ge_u32 s15, s11
	s_cselect_b32 s16, -1, 0
	s_cmp_ge_u32 s14, s10
	s_cselect_b32 s10, -1, 0
	s_cmp_eq_u32 s15, s11
	s_cselect_b32 s10, s10, s16
	s_cmp_lg_u32 s10, 0
	s_cselect_b32 s11, s19, s5
	s_cselect_b32 s10, s18, s3
	s_xor_b64 s[8:9], s[12:13], s[8:9]
	s_xor_b64 s[10:11], s[10:11], s[8:9]
	s_sub_u32 s8, s10, s8
	v_cvt_f32_u32_e32 v1, s56
	s_cbranch_execnz .LBB0_510

.LBB0_600:
	s_setprio 0
	s_cmp_gt_i32 s60, 8
	s_cselect_b64 s[4:5], -1, 0
	s_cmp_lt_i32 s61, 9
	s_cselect_b64 s[6:7], -1, 0
	s_or_b64 s[4:5], s[4:5], s[6:7]
	s_and_b64 vcc, exec, s[4:5]
	s_cbranch_vccnz .LBB0_761
	s_cmpk_gt_i32 s2, 0xff
	s_cbranch_scc1 .LBB0_696
	v_readlane_b32 s3, v255, 6
	s_lshl_b32 s4, s3, 5
	s_lshl_b32 s3, s3, 2
	s_add_i32 s3, s3, 0
	v_readlane_b32 s5, v255, 5
	s_cmp_lt_u32 s5, 64
	s_cselect_b64 s[46:47], -1, 0
	s_cmpk_gt_u32 s5, 0x7f
	s_cselect_b64 s[50:51], -1, 0
	s_cmpk_gt_u32 s5, 0xbf
	s_cselect_b64 s[58:59], -1, 0
	s_cmpk_gt_u32 s5, 0xff
	s_cselect_b64 s[72:73], -1, 0
	s_cmpk_gt_u32 s5, 0x13f
	s_cselect_b64 s[86:87], -1, 0
	s_cmpk_gt_u32 s5, 0x17f
	s_cselect_b64 s[88:89], -1, 0
	s_cmpk_gt_u32 s5, 0x1bf
	s_cselect_b64 s[90:91], -1, 0
	s_cmpk_gt_u32 s5, 0x1ff
	s_waitcnt vmcnt(0)
	v_mbcnt_lo_u32_b32 v2, -1, 0
	v_and_b32_e32 v1, 63, v0
	s_mov_b32 s43, 0
	s_movk_i32 s41, 0x1ff
	s_cselect_b64 s[92:93], -1, 0
	s_add_i32 s45, s4, 0
	v_mov_b32_e32 v44, -1
	v_mbcnt_hi_u32_b32 v45, -1, v2
	v_mov_b32_e32 v46, 0
	s_mov_b32 s94, s2
	s_branch .LBB0_606

.LBB0_1390:
	s_add_u32 s50, s52, 0x136000
	s_addc_u32 s51, s53, 0
	s_cmp_gt_i32 s60, 19
	s_cselect_b64 s[4:5], -1, 0
	s_cmp_lt_i32 s61, 20
	s_cselect_b64 s[6:7], -1, 0
	s_or_b64 s[4:5], s[4:5], s[6:7]
	s_and_b64 vcc, exec, s[4:5]
	s_cbranch_vccnz .LBB0_1484
	v_readlane_b32 s100, v255, 6
	s_cmp_lg_u32 s100, 0
	s_cbranch_scc1 .Ln2prio_2
	s_setprio 2
.Ln2prio_2:
	s_mul_hi_i32 s5, s2, 0x880
	s_mul_i32 s4, s2, 0x880
	s_ashr_i32 s57, s56, 31
	s_or_b64 s[6:7], s[4:5], s[56:57]
	s_mov_b32 s6, 0
	v_and_b32_e32 v196, 63, v0
	s_cmp_lg_u64 s[6:7], 0
	s_cbranch_scc0 .LBB0_1444
	s_ashr_i32 s6, s57, 31
	s_add_u32 s8, s56, s6
	s_mov_b32 s7, s6
	s_addc_u32 s9, s57, s6
	s_xor_b64 s[10:11], s[8:9], s[6:7]
	v_cvt_f32_u32_e32 v1, s10
	s_waitcnt vmcnt(0)
	v_cvt_f32_u32_e32 v2, s11
	s_sub_u32 s3, 0, s10
	s_subb_u32 s14, 0, s11
	v_fmamk_f32 v1, v2, 0x4f800000, v1
	v_rcp_f32_e32 v1, v1
	s_nop 0
	v_mul_f32_e32 v1, 0x5f7ffffc, v1
	v_mul_f32_e32 v2, 0x2f800000, v1
	v_trunc_f32_e32 v2, v2
	v_fmamk_f32 v1, v2, 0xcf800000, v1
	v_cvt_u32_f32_e32 v2, v2
	v_cvt_u32_f32_e32 v1, v1
	v_readfirstlane_b32 s15, v2
	v_readfirstlane_b32 s12, v1
	s_mul_i32 s13, s3, s15
	s_mul_hi_u32 s17, s3, s12
	s_mul_i32 s16, s14, s12
	s_add_i32 s13, s17, s13
	s_add_i32 s13, s13, s16
	s_mul_i32 s18, s3, s12
	s_mul_i32 s17, s12, s13
	s_mul_hi_u32 s19, s12, s18
	s_mul_hi_u32 s16, s12, s13
	s_add_u32 s17, s19, s17
	s_addc_u32 s16, 0, s16
	s_mul_hi_u32 s20, s15, s18
	s_mul_i32 s18, s15, s18
	s_add_u32 s17, s17, s18
	s_mul_hi_u32 s19, s15, s13
	s_addc_u32 s16, s16, s20
	s_addc_u32 s17, s19, 0
	s_mul_i32 s13, s15, s13
	s_add_u32 s13, s16, s13
	s_addc_u32 s16, 0, s17
	s_add_u32 s17, s12, s13
	s_cselect_b64 s[12:13], -1, 0
	s_cmp_lg_u64 s[12:13], 0
	s_addc_u32 s15, s15, s16
	s_mul_i32 s12, s3, s15
	s_mul_hi_u32 s13, s3, s17
	s_add_i32 s12, s13, s12
	s_mul_i32 s14, s14, s17
	s_add_i32 s12, s12, s14
	s_mul_i32 s3, s3, s17
	s_mul_hi_u32 s14, s15, s3
	s_mul_i32 s16, s15, s3
	s_mul_i32 s19, s17, s12
	s_mul_hi_u32 s3, s17, s3
	s_mul_hi_u32 s18, s17, s12
	s_add_u32 s3, s3, s19
	s_addc_u32 s18, 0, s18
	s_add_u32 s3, s3, s16
	s_mul_hi_u32 s13, s15, s12
	s_addc_u32 s3, s18, s14
	s_addc_u32 s13, s13, 0
	s_mul_i32 s12, s15, s12
	s_add_u32 s3, s3, s12
	s_addc_u32 s14, 0, s13
	s_add_u32 s3, s17, s3
	s_cselect_b64 s[12:13], -1, 0
	s_cmp_lg_u64 s[12:13], 0
	s_addc_u32 s16, s15, s14
	s_ashr_i32 s12, s5, 31
	s_add_u32 s14, s4, s12
	s_mov_b32 s13, s12
	s_addc_u32 s15, s5, s12
	s_xor_b64 s[14:15], s[14:15], s[12:13]
	s_mul_i32 s17, s14, s16
	s_mul_hi_u32 s18, s14, s3
	s_mul_hi_u32 s5, s14, s16
	s_add_u32 s17, s18, s17
	s_addc_u32 s5, 0, s5
	s_mul_hi_u32 s19, s15, s3
	s_mul_i32 s3, s15, s3
	s_add_u32 s3, s17, s3
	s_mul_hi_u32 s18, s15, s16
	s_addc_u32 s3, s5, s19
	s_addc_u32 s5, s18, 0
	s_mul_i32 s16, s15, s16
	s_add_u32 s3, s3, s16
	s_addc_u32 s5, 0, s5
	s_mul_i32 s16, s10, s5
	s_mul_hi_u32 s17, s10, s3
	s_add_i32 s16, s17, s16
	s_mul_i32 s17, s11, s3
	s_add_i32 s20, s16, s17
	s_sub_i32 s18, s15, s20
	s_mul_i32 s16, s10, s3
	s_sub_u32 s14, s14, s16
	s_cselect_b64 s[16:17], -1, 0
	s_cmp_lg_u64 s[16:17], 0
	s_subb_u32 s21, s18, s11
	s_sub_u32 s22, s14, s10
	s_cselect_b64 s[18:19], -1, 0
	s_cmp_lg_u64 s[18:19], 0
	s_subb_u32 s18, s21, 0
	s_cmp_ge_u32 s18, s11
	s_cselect_b32 s19, -1, 0
	s_cmp_ge_u32 s22, s10
	s_cselect_b32 s21, -1, 0
	s_cmp_eq_u32 s18, s11
	s_cselect_b32 s18, s21, s19
	s_add_u32 s19, s3, 1
	s_addc_u32 s21, s5, 0
	s_add_u32 s22, s3, 2
	s_addc_u32 s23, s5, 0
	s_cmp_lg_u32 s18, 0
	s_cselect_b32 s18, s22, s19
	s_cselect_b32 s19, s23, s21
	s_cmp_lg_u64 s[16:17], 0
	s_subb_u32 s15, s15, s20
	s_cmp_ge_u32 s15, s11
	s_cselect_b32 s16, -1, 0
	s_cmp_ge_u32 s14, s10
	s_cselect_b32 s10, -1, 0
	s_cmp_eq_u32 s15, s11
	s_cselect_b32 s10, s10, s16
	s_cmp_lg_u32 s10, 0
	s_cselect_b32 s11, s19, s5
	s_cselect_b32 s10, s18, s3
	s_xor_b64 s[6:7], s[12:13], s[6:7]
	s_xor_b64 s[10:11], s[10:11], s[6:7]
	s_sub_u32 s6, s10, s6
	v_cvt_f32_u32_e32 v1, s56
	s_cbranch_execnz .LBB0_1394

.LBB0_1484:
	s_setprio 0
	s_cmp_gt_i32 s60, 20
	s_cselect_b64 s[4:5], -1, 0
	s_cmp_lt_i32 s61, 21
	s_cselect_b64 s[6:7], -1, 0
	s_or_b64 s[4:5], s[4:5], s[6:7]
	s_and_b64 vcc, exec, s[4:5]
	s_cbranch_vccnz .LBB0_1645
	s_cmpk_gt_i32 s2, 0xff
	s_cbranch_scc1 .LBB0_1580
	v_readlane_b32 s3, v255, 6
	s_lshl_b32 s4, s3, 5
	s_lshl_b32 s3, s3, 2
	s_add_i32 s3, s3, 0
	v_readlane_b32 s5, v255, 5
	s_cmp_lt_u32 s5, 64
	s_cselect_b64 s[46:47], -1, 0
	s_cmpk_gt_u32 s5, 0x7f
	s_cselect_b64 s[58:59], -1, 0
	s_cmpk_gt_u32 s5, 0xbf
	s_cselect_b64 s[72:73], -1, 0
	s_cmpk_gt_u32 s5, 0xff
	s_cselect_b64 s[84:85], -1, 0
	s_cmpk_gt_u32 s5, 0x13f
	s_cselect_b64 s[86:87], -1, 0
	s_cmpk_gt_u32 s5, 0x17f
	s_cselect_b64 s[88:89], -1, 0
	s_cmpk_gt_u32 s5, 0x1bf
	s_cselect_b64 s[90:91], -1, 0
	s_cmpk_gt_u32 s5, 0x1ff
	s_waitcnt vmcnt(0)
	v_mbcnt_lo_u32_b32 v2, -1, 0
	v_and_b32_e32 v1, 63, v0
	s_mov_b32 s43, 0
	s_movk_i32 s41, 0x1ff
	s_cselect_b64 s[92:93], -1, 0
	s_add_i32 s45, s4, 0
	v_mov_b32_e32 v44, -1
	v_mbcnt_hi_u32_b32 v45, -1, v2
	v_mov_b32_e32 v46, 0
	s_mov_b32 s94, s2
	s_branch .LBB0_1490

.LBB0_2207:
	s_add_u32 s50, s52, 0x16c000
	s_addc_u32 s51, s53, 0
	s_cmp_gt_i32 s60, 31
	s_cselect_b64 s[4:5], -1, 0
	s_cmp_lt_i32 s61, 32
	s_cselect_b64 s[6:7], -1, 0
	s_or_b64 s[4:5], s[4:5], s[6:7]
	s_and_b64 vcc, exec, s[4:5]
	s_cbranch_vccnz .LBB0_2301
	v_readlane_b32 s100, v255, 6
	s_cmp_lg_u32 s100, 0
	s_cbranch_scc1 .Ln2prio_1
	s_setprio 2
.Ln2prio_1:
	s_ashr_i32 s3, s2, 31
	s_lshl_b64 s[4:5], s[2:3], 11
	s_ashr_i32 s57, s56, 31
	s_or_b64 s[6:7], s[4:5], s[56:57]
	s_mov_b32 s6, 0
	v_and_b32_e32 v196, 63, v0
	s_cmp_lg_u64 s[6:7], 0
	s_cbranch_scc0 .LBB0_2261
	s_ashr_i32 s6, s57, 31
	s_add_u32 s8, s56, s6
	s_mov_b32 s7, s6
	s_addc_u32 s9, s57, s6
	s_xor_b64 s[10:11], s[8:9], s[6:7]
	v_cvt_f32_u32_e32 v1, s10
	s_waitcnt vmcnt(0)
	v_cvt_f32_u32_e32 v2, s11
	s_sub_u32 s14, 0, s10
	s_subb_u32 s15, 0, s11
	v_fmamk_f32 v1, v2, 0x4f800000, v1
	v_rcp_f32_e32 v1, v1
	s_nop 0
	v_mul_f32_e32 v1, 0x5f7ffffc, v1
	v_mul_f32_e32 v2, 0x2f800000, v1
	v_trunc_f32_e32 v2, v2
	v_fmamk_f32 v1, v2, 0xcf800000, v1
	v_cvt_u32_f32_e32 v2, v2
	v_cvt_u32_f32_e32 v1, v1
	v_readfirstlane_b32 s16, v2
	v_readfirstlane_b32 s12, v1
	s_mul_i32 s13, s14, s16
	s_mul_hi_u32 s18, s14, s12
	s_mul_i32 s17, s15, s12
	s_add_i32 s13, s18, s13
	s_add_i32 s13, s13, s17
	s_mul_i32 s19, s14, s12
	s_mul_i32 s18, s12, s13
	s_mul_hi_u32 s20, s12, s19
	s_mul_hi_u32 s17, s12, s13
	s_add_u32 s18, s20, s18
	s_addc_u32 s17, 0, s17
	s_mul_hi_u32 s21, s16, s19
	s_mul_i32 s19, s16, s19
	s_add_u32 s18, s18, s19
	s_mul_hi_u32 s20, s16, s13
	s_addc_u32 s17, s17, s21
	s_addc_u32 s18, s20, 0
	s_mul_i32 s13, s16, s13
	s_add_u32 s13, s17, s13
	s_addc_u32 s17, 0, s18
	s_add_u32 s18, s12, s13
	s_cselect_b64 s[12:13], -1, 0
	s_cmp_lg_u64 s[12:13], 0
	s_addc_u32 s16, s16, s17
	s_mul_i32 s12, s14, s16
	s_mul_hi_u32 s13, s14, s18
	s_add_i32 s12, s13, s12
	s_mul_i32 s15, s15, s18
	s_add_i32 s12, s12, s15
	s_mul_i32 s14, s14, s18
	s_mul_hi_u32 s15, s16, s14
	s_mul_i32 s17, s16, s14
	s_mul_i32 s20, s18, s12
	s_mul_hi_u32 s14, s18, s14
	s_mul_hi_u32 s19, s18, s12
	s_add_u32 s14, s14, s20
	s_addc_u32 s19, 0, s19
	s_add_u32 s14, s14, s17
	s_mul_hi_u32 s13, s16, s12
	s_addc_u32 s14, s19, s15
	s_addc_u32 s13, s13, 0
	s_mul_i32 s12, s16, s12
	s_add_u32 s12, s14, s12
	s_addc_u32 s14, 0, s13
	s_add_u32 s17, s18, s12
	s_cselect_b64 s[12:13], -1, 0
	s_cmp_lg_u64 s[12:13], 0
	s_addc_u32 s16, s16, s14
	s_ashr_i32 s12, s5, 31
	s_add_u32 s14, s4, s12
	s_mov_b32 s13, s12
	s_addc_u32 s15, s5, s12
	s_xor_b64 s[14:15], s[14:15], s[12:13]
	s_mul_i32 s18, s14, s16
	s_mul_hi_u32 s19, s14, s17
	s_mul_hi_u32 s5, s14, s16
	s_add_u32 s18, s19, s18
	s_addc_u32 s5, 0, s5
	s_mul_hi_u32 s20, s15, s17
	s_mul_i32 s17, s15, s17
	s_add_u32 s17, s18, s17
	s_mul_hi_u32 s19, s15, s16
	s_addc_u32 s5, s5, s20
	s_addc_u32 s17, s19, 0
	s_mul_i32 s16, s15, s16
	s_add_u32 s5, s5, s16
	s_addc_u32 s20, 0, s17
	s_mul_i32 s16, s10, s20
	s_mul_hi_u32 s17, s10, s5
	s_add_i32 s16, s17, s16
	s_mul_i32 s17, s11, s5
	s_add_i32 s21, s16, s17
	s_sub_i32 s18, s15, s21
	s_mul_i32 s16, s10, s5
	s_sub_u32 s14, s14, s16
	s_cselect_b64 s[16:17], -1, 0
	s_cmp_lg_u64 s[16:17], 0
	s_subb_u32 s22, s18, s11
	s_sub_u32 s23, s14, s10
	s_cselect_b64 s[18:19], -1, 0
	s_cmp_lg_u64 s[18:19], 0
	s_subb_u32 s18, s22, 0
	s_cmp_ge_u32 s18, s11
	s_cselect_b32 s19, -1, 0
	s_cmp_ge_u32 s23, s10
	s_cselect_b32 s22, -1, 0
	s_cmp_eq_u32 s18, s11
	s_cselect_b32 s18, s22, s19
	s_add_u32 s19, s5, 1
	s_addc_u32 s22, s20, 0
	s_add_u32 s23, s5, 2
	s_addc_u32 s24, s20, 0
	s_cmp_lg_u32 s18, 0
	s_cselect_b32 s18, s23, s19
	s_cselect_b32 s19, s24, s22
	s_cmp_lg_u64 s[16:17], 0
	s_subb_u32 s15, s15, s21
	s_cmp_ge_u32 s15, s11
	s_cselect_b32 s16, -1, 0
	s_cmp_ge_u32 s14, s10
	s_cselect_b32 s10, -1, 0
	s_cmp_eq_u32 s15, s11
	s_cselect_b32 s10, s10, s16
	s_cmp_lg_u32 s10, 0
	s_cselect_b32 s11, s19, s20
	s_cselect_b32 s10, s18, s5
	s_xor_b64 s[6:7], s[12:13], s[6:7]
	s_xor_b64 s[10:11], s[10:11], s[6:7]
	s_sub_u32 s6, s10, s6
	v_cvt_f32_u32_e32 v1, s56
	s_cbranch_execnz .LBB0_2211

.LBB0_2301:
	s_setprio 0
	s_cmp_gt_i32 s60, 32
	s_cselect_b64 s[4:5], -1, 0
	s_cmp_lt_i32 s61, 33
	s_cselect_b64 s[6:7], -1, 0
	s_or_b64 s[4:5], s[4:5], s[6:7]
	s_and_b64 vcc, exec, s[4:5]
	s_cbranch_vccnz .LBB0_2414
	s_cmpk_gt_i32 s2, 0x7f
	s_cbranch_scc1 .LBB0_2349
	v_readlane_b32 s3, v255, 6
	s_lshl_b32 s4, s3, 5
	s_lshl_b32 s3, s3, 2
	s_add_i32 s3, s3, 0
	v_readlane_b32 s5, v255, 5
	s_cmp_lt_u32 s5, 64
	s_cselect_b64 s[42:43], -1, 0
	s_cmpk_gt_u32 s5, 0x7f
	s_cselect_b64 s[46:47], -1, 0
	s_cmpk_gt_u32 s5, 0xbf
	s_cselect_b64 s[58:59], -1, 0
	s_cmpk_gt_u32 s5, 0xff
	s_cselect_b64 s[72:73], -1, 0
	s_cmpk_gt_u32 s5, 0x13f
	s_cselect_b64 s[84:85], -1, 0
	s_cmpk_gt_u32 s5, 0x17f
	s_cselect_b64 s[86:87], -1, 0
	s_cmpk_gt_u32 s5, 0x1bf
	s_cselect_b64 s[88:89], -1, 0
	s_cmpk_gt_u32 s5, 0x1ff
	s_waitcnt vmcnt(0)
	v_mbcnt_lo_u32_b32 v2, -1, 0
	v_and_b32_e32 v1, 63, v0
	s_movk_i32 s41, 0x1ff
	s_cselect_b64 s[90:91], -1, 0
	s_add_i32 s45, s4, 0
	v_mbcnt_hi_u32_b32 v44, -1, v2
	v_mov_b32_e32 v45, -1
	v_mov_b32_e32 v46, 0
	s_mov_b32 s92, s2
	s_branch .LBB0_2306

.LBB0_2883:
	s_add_u32 s48, s52, 0x1a2000
	s_addc_u32 s49, s53, 0
	s_cmp_gt_i32 s60, 43
	s_cselect_b64 s[4:5], -1, 0
	s_cmp_lt_i32 s61, 44
	s_cselect_b64 s[6:7], -1, 0
	s_or_b64 s[4:5], s[4:5], s[6:7]
	s_and_b64 vcc, exec, s[4:5]
	s_cbranch_vccnz .LBB0_2977
	v_readlane_b32 s100, v255, 6
	s_cmp_lg_u32 s100, 0
	s_cbranch_scc1 .Ln2prio_0
	s_setprio 2
.Ln2prio_0:
	s_ashr_i32 s3, s2, 31
	s_lshl_b64 s[4:5], s[2:3], 11
	s_ashr_i32 s57, s56, 31
	s_or_b64 s[6:7], s[4:5], s[56:57]
	s_mov_b32 s6, 0
	v_mov_b32_e32 v196, v1
	s_cmp_lg_u64 s[6:7], 0
	s_cbranch_scc0 .LBB0_2937
	s_ashr_i32 s6, s57, 31
	s_add_u32 s8, s56, s6
	s_mov_b32 s7, s6
	s_addc_u32 s9, s57, s6
	s_xor_b64 s[10:11], s[8:9], s[6:7]
	s_waitcnt vmcnt(0)
	v_cvt_f32_u32_e32 v2, s10
	v_cvt_f32_u32_e32 v3, s11
	s_sub_u32 s14, 0, s10
	s_subb_u32 s15, 0, s11
	v_fmamk_f32 v2, v3, 0x4f800000, v2
	v_rcp_f32_e32 v2, v2
	s_nop 0
	v_mul_f32_e32 v2, 0x5f7ffffc, v2
	v_mul_f32_e32 v3, 0x2f800000, v2
	v_trunc_f32_e32 v3, v3
	v_fmamk_f32 v2, v3, 0xcf800000, v2
	v_cvt_u32_f32_e32 v3, v3
	v_cvt_u32_f32_e32 v2, v2
	v_readfirstlane_b32 s16, v3
	v_readfirstlane_b32 s12, v2
	s_mul_i32 s13, s14, s16
	s_mul_hi_u32 s18, s14, s12
	s_mul_i32 s17, s15, s12
	s_add_i32 s13, s18, s13
	s_add_i32 s13, s13, s17
	s_mul_i32 s19, s14, s12
	s_mul_i32 s18, s12, s13
	s_mul_hi_u32 s20, s12, s19
	s_mul_hi_u32 s17, s12, s13
	s_add_u32 s18, s20, s18
	s_addc_u32 s17, 0, s17
	s_mul_hi_u32 s21, s16, s19
	s_mul_i32 s19, s16, s19
	s_add_u32 s18, s18, s19
	s_mul_hi_u32 s20, s16, s13
	s_addc_u32 s17, s17, s21
	s_addc_u32 s18, s20, 0
	s_mul_i32 s13, s16, s13
	s_add_u32 s13, s17, s13
	s_addc_u32 s17, 0, s18
	s_add_u32 s18, s12, s13
	s_cselect_b64 s[12:13], -1, 0
	s_cmp_lg_u64 s[12:13], 0
	s_addc_u32 s16, s16, s17
	s_mul_i32 s12, s14, s16
	s_mul_hi_u32 s13, s14, s18
	s_add_i32 s12, s13, s12
	s_mul_i32 s15, s15, s18
	s_add_i32 s12, s12, s15
	s_mul_i32 s14, s14, s18
	s_mul_hi_u32 s15, s16, s14
	s_mul_i32 s17, s16, s14
	s_mul_i32 s20, s18, s12
	s_mul_hi_u32 s14, s18, s14
	s_mul_hi_u32 s19, s18, s12
	s_add_u32 s14, s14, s20
	s_addc_u32 s19, 0, s19
	s_add_u32 s14, s14, s17
	s_mul_hi_u32 s13, s16, s12
	s_addc_u32 s14, s19, s15
	s_addc_u32 s13, s13, 0
	s_mul_i32 s12, s16, s12
	s_add_u32 s12, s14, s12
	s_addc_u32 s14, 0, s13
	s_add_u32 s17, s18, s12
	s_cselect_b64 s[12:13], -1, 0
	s_cmp_lg_u64 s[12:13], 0
	s_addc_u32 s16, s16, s14
	s_ashr_i32 s12, s5, 31
	s_add_u32 s14, s4, s12
	s_mov_b32 s13, s12
	s_addc_u32 s15, s5, s12
	s_xor_b64 s[14:15], s[14:15], s[12:13]
	s_mul_i32 s18, s14, s16
	s_mul_hi_u32 s19, s14, s17
	s_mul_hi_u32 s5, s14, s16
	s_add_u32 s18, s19, s18
	s_addc_u32 s5, 0, s5
	s_mul_hi_u32 s20, s15, s17
	s_mul_i32 s17, s15, s17
	s_add_u32 s17, s18, s17
	s_mul_hi_u32 s19, s15, s16
	s_addc_u32 s5, s5, s20
	s_addc_u32 s17, s19, 0
	s_mul_i32 s16, s15, s16
	s_add_u32 s5, s5, s16
	s_addc_u32 s20, 0, s17
	s_mul_i32 s16, s10, s20
	s_mul_hi_u32 s17, s10, s5
	s_add_i32 s16, s17, s16
	s_mul_i32 s17, s11, s5
	s_add_i32 s21, s16, s17
	s_sub_i32 s18, s15, s21
	s_mul_i32 s16, s10, s5
	s_sub_u32 s14, s14, s16
	s_cselect_b64 s[16:17], -1, 0
	s_cmp_lg_u64 s[16:17], 0
	s_subb_u32 s22, s18, s11
	s_sub_u32 s23, s14, s10
	s_cselect_b64 s[18:19], -1, 0
	s_cmp_lg_u64 s[18:19], 0
	s_subb_u32 s18, s22, 0
	s_cmp_ge_u32 s18, s11
	s_cselect_b32 s19, -1, 0
	s_cmp_ge_u32 s23, s10
	s_cselect_b32 s22, -1, 0
	s_cmp_eq_u32 s18, s11
	s_cselect_b32 s18, s22, s19
	s_add_u32 s19, s5, 1
	s_addc_u32 s22, s20, 0
	s_add_u32 s23, s5, 2
	s_addc_u32 s24, s20, 0
	s_cmp_lg_u32 s18, 0
	s_cselect_b32 s18, s23, s19
	s_cselect_b32 s19, s24, s22
	s_cmp_lg_u64 s[16:17], 0
	s_subb_u32 s15, s15, s21
	s_cmp_ge_u32 s15, s11
	s_cselect_b32 s16, -1, 0
	s_cmp_ge_u32 s14, s10
	s_cselect_b32 s10, -1, 0
	s_cmp_eq_u32 s15, s11
	s_cselect_b32 s10, s10, s16
	s_cmp_lg_u32 s10, 0
	s_cselect_b32 s11, s19, s20
	s_cselect_b32 s10, s18, s5
	s_xor_b64 s[6:7], s[12:13], s[6:7]
	s_xor_b64 s[10:11], s[10:11], s[6:7]
	s_sub_u32 s6, s10, s6
	v_cvt_f32_u32_e32 v2, s56
	s_cbranch_execnz .LBB0_2887

.LBB0_2977:
	s_setprio 0
	s_cmp_gt_i32 s60, 44
	s_cselect_b64 s[4:5], -1, 0
	s_cmp_lt_i32 s61, 45
	s_cselect_b64 s[6:7], -1, 0
	s_or_b64 s[4:5], s[4:5], s[6:7]
	s_and_b64 vcc, exec, s[4:5]
	s_cbranch_vccnz .LBB0_3090
	s_cmpk_gt_i32 s2, 0x7f
	s_cbranch_scc1 .LBB0_3025
	v_readlane_b32 s3, v255, 6
	s_lshl_b32 s4, s3, 5
	s_lshl_b32 s3, s3, 2
	s_add_i32 s3, s3, 0
	v_readlane_b32 s5, v255, 5
	s_cmp_lt_u32 s5, 64
	s_cselect_b64 s[42:43], -1, 0
	s_cmpk_gt_u32 s5, 0x7f
	s_cselect_b64 s[46:47], -1, 0
	s_cmpk_gt_u32 s5, 0xbf
	s_cselect_b64 s[50:51], -1, 0
	s_cmpk_gt_u32 s5, 0xff
	s_cselect_b64 s[58:59], -1, 0
	s_cmpk_gt_u32 s5, 0x13f
	s_cselect_b64 s[72:73], -1, 0
	s_cmpk_gt_u32 s5, 0x17f
	s_cselect_b64 s[78:79], -1, 0
	s_cmpk_gt_u32 s5, 0x1bf
	s_cselect_b64 s[80:81], -1, 0
	s_cmpk_gt_u32 s5, 0x1ff
	s_waitcnt vmcnt(0)
	v_mbcnt_lo_u32_b32 v2, -1, 0
	s_movk_i32 s41, 0x1ff
	s_cselect_b64 s[82:83], -1, 0
	s_add_i32 s45, s4, 0
	v_mbcnt_hi_u32_b32 v44, -1, v2
	v_mov_b32_e32 v45, -1
	v_mov_b32_e32 v46, 0
	s_mov_b32 s84, s2
	s_branch .LBB0_2982
